# grid barrier: waiters watch the cross-XCD arrival counter itself (no separate release word), barrier index kept in a spare lane instead of two integer divisions; LN row-stat exchange: dropped the L1 i
# speedup vs baseline: 1.0254x; 1.0029x over previous
; #define LAS __attribute__((address_space(3)))
; __global__ void __launch_bounds__(NWAVES * 64, 2) mega_fwd(Args args) {
;     extern __shared__ __attribute__((aligned(16))) unsigned char lds_raw[];
;     LAS unsigned char* lds = (LAS unsigned char*)lds_raw;
;     cg::grid_group grid = cg::this_grid();
;     const int tid = threadIdx.x, lane = tid & 63, wave = __builtin_amdgcn_readfirstlane(tid >> 6);
;     const int G = gridDim.x, gw = blockIdx.x * NWAVES + wave, NGW = G * NWAVES;
;     ...
;     const int lo = args.ph_lo, hi = args.ph_hi;
;     volatile LAS unsigned* bar_st = (volatile LAS unsigned*)(lds + 147200);
;     if (tid == 0) { bar_st[0] = 0u; bar_st[1] = 0u; }
;     __syncthreads();
_Z8mega_fwd4Args:
	v_writelane_b32 v244, 0, 63
	s_load_dwordx4 s[64:67], s[0:1], 0x110
	s_load_dwordx2 s[88:89], s[0:1], 0x120
	s_load_dword s92, s[0:1], 0x128
	s_mov_b64 s[56:57], s[0:1]
	s_add_u32 s6, s56, 0x120
	v_and_b32_e32 v154, 0x3ff, v0
	s_addc_u32 s7, s57, 0
	v_readfirstlane_b32 s3, v154
	v_cmp_eq_u32_e64 s[80:81], 0, v154
	s_and_saveexec_b64 s[0:1], s[80:81]
	s_cbranch_execz .LBB0_2
	s_add_i32 s4, 0, 0x23f00
	v_mov_b32_e32 v1, 0
	v_mov_b32_e32 v2, s4
	s_add_i32 s4, 0, 0x23f04
	ds_write_b32 v2, v1
	v_mov_b32_e32 v2, s4
	ds_write_b32 v2, v1

; __device__ __forceinline__ unsigned xb_ld(unsigned* p)              { return __hip_atomic_load(p, __ATOMIC_RELAXED, __HIP_MEMORY_SCOPE_AGENT); }
; __device__ __forceinline__ unsigned xb_add(unsigned* p, unsigned v) { return __hip_atomic_fetch_add(p, v, __ATOMIC_RELAXED, __HIP_MEMORY_SCOPE_AGENT); }
; #define XB_SPIN(cond, bar) do { unsigned _sp = 0; while (cond) { __builtin_amdgcn_s_sleep(1); \
;     if ((++_sp & 255u) == 0u) { if (xb_ld(&(bar)[XB_TMO])) break; if (_sp > XB_SPIN_CAP) { atomicAdd(&(bar)[XB_TMO], 1u); break; } } } } while (0)
; __device__ __forceinline__ void xcd_barrier(const XcdBarrier& b) {
;     ...
;         const unsigned old = xb_add(&bar[XB_XSUB(b.x)], 1u);
;         const unsigned gen = old / nloc;
;         if (old + 1u == (gen + 1u) * nloc) {
;             __builtin_amdgcn_fence(__ATOMIC_RELEASE, "agent");
;             asm volatile("s_waitcnt vmcnt(0)" ::: "memory");
;             const unsigned og = xb_add(&bar[XB_TOP], 1u);
;             const unsigned tg = og / nx;
;             if (og + 1u == (tg + 1u) * nx) xb_add(&bar[XB_TOPGEN], 1u);
;             else XB_SPIN(xb_ld(&bar[XB_TOPGEN]) == tg, bar);
;             __builtin_amdgcn_fence(__ATOMIC_ACQUIRE, "agent");
;             xb_add(&bar[XB_XGEN(b.x)], 1u);
;             asm volatile("s_waitcnt vmcnt(0)" ::: "memory");
;         } else {
;             XB_SPIN(xb_ld(&bar[XB_XGEN(b.x)]) == gen, bar);
;             __builtin_amdgcn_fence(__ATOMIC_ACQUIRE, "agent");
;             asm volatile("s_waitcnt vmcnt(0)" ::: "memory");
;         }
.LBB0_70:
	s_or_b64 exec, exec, s[10:11]
	s_waitcnt vmcnt(0)
	v_readfirstlane_b32 s0, v3
	v_add_u32_e32 v5, s0, v1
	v_readlane_b32 s0, v244, 63
	v_add_u32_e32 v3, 1, v5
	v_mov_b32_e32 v1, s0
	v_mad_u32_u24 v2, v1, v2, v2
	s_add_i32 s0, s0, 1
	v_writelane_b32 v244, s0, 63
	v_cmp_ne_u32_e32 vcc, v3, v2
	s_and_saveexec_b64 s[0:1], vcc
	s_xor_b64 s[10:11], exec, s[0:1]
	s_cbranch_execz .LBB0_84
	s_waitcnt lgkmcnt(0)
	buffer_inv sc1
	v_mad_u32_u24 v3, v1, v0, v0
	v_mov_b32_e32 v0, 0x3400
	global_load_dword v0, v0, s[86:87] sc1
	s_add_u32 s14, s86, 0x3400
	s_addc_u32 s15, s87, 0
	s_waitcnt vmcnt(0)
	v_cmp_lt_u32_e32 vcc, v0, v3
	s_and_saveexec_b64 s[12:13], vcc
	s_cbranch_execz .LBB0_83
	s_mov_b32 s3, 1
	s_mov_b64 s[16:17], 0
	v_mov_b32_e32 v0, 0
	s_branch .LBB0_74

; __device__ __forceinline__ unsigned xb_ld(unsigned* p)              { return __hip_atomic_load(p, __ATOMIC_RELAXED, __HIP_MEMORY_SCOPE_AGENT); }
; #define XB_SPIN(cond, bar) do { unsigned _sp = 0; while (cond) { __builtin_amdgcn_s_sleep(1); \
;     if ((++_sp & 255u) == 0u) { if (xb_ld(&(bar)[XB_TMO])) break; if (_sp > XB_SPIN_CAP) { atomicAdd(&(bar)[XB_TMO], 1u); break; } } } } while (0)
; __device__ __forceinline__ void xcd_barrier(const XcdBarrier& b) {
;     ...
;             XB_SPIN(xb_ld(&bar[XB_XGEN(b.x)]) == gen, bar);
.LBB0_76:
	global_load_dword v2, v0, s[14:15] sc1
	s_add_i32 s3, s3, 1
	s_mov_b64 s[20:21], -1
	s_waitcnt vmcnt(0)
	v_cmp_ge_u32_e32 vcc, v2, v3
	s_orn2_b64 s[0:1], vcc, exec
	s_branch .LBB0_73

; __device__ __forceinline__ unsigned xb_ld(unsigned* p)              { return __hip_atomic_load(p, __ATOMIC_RELAXED, __HIP_MEMORY_SCOPE_AGENT); }
; __device__ __forceinline__ unsigned xb_add(unsigned* p, unsigned v) { return __hip_atomic_fetch_add(p, v, __ATOMIC_RELAXED, __HIP_MEMORY_SCOPE_AGENT); }
; #define XB_SPIN(cond, bar) do { unsigned _sp = 0; while (cond) { __builtin_amdgcn_s_sleep(1); \
;     if ((++_sp & 255u) == 0u) { if (xb_ld(&(bar)[XB_TMO])) break; if (_sp > XB_SPIN_CAP) { atomicAdd(&(bar)[XB_TMO], 1u); break; } } } } while (0)
; __device__ __forceinline__ void xcd_barrier(const XcdBarrier& b) {
;     ...
;             const unsigned og = xb_add(&bar[XB_TOP], 1u);
;             const unsigned tg = og / nx;
;             if (og + 1u == (tg + 1u) * nx) xb_add(&bar[XB_TOPGEN], 1u);
;             else XB_SPIN(xb_ld(&bar[XB_TOPGEN]) == tg, bar);
;             __builtin_amdgcn_fence(__ATOMIC_ACQUIRE, "agent");
.LBB0_87:
	s_or_b64 exec, exec, s[10:11]
	s_waitcnt vmcnt(0)
	v_readfirstlane_b32 s0, v2
	s_add_u32 s12, s86, 0x3400
	s_addc_u32 s13, s87, 0
	v_add_u32_e32 v1, s0, v1
	v_add_u32_e32 v4, 1, v1
	s_mov_b64 s[0:1], 0
	v_readlane_b32 s10, v244, 63
	s_nop 0
	v_mul_u32_u24_e32 v0, s10, v0
	v_cmp_ne_u32_e32 vcc, v4, v0
	v_mov_b32_e32 v3, v0
	v_mov_b64_e32 v[0:1], s[12:13]
	s_and_saveexec_b64 s[10:11], vcc
	s_cbranch_execz .LBB0_99
	v_mov_b32_e32 v0, 0
	global_load_dword v1, v0, s[12:13] sc1
	s_mov_b64 s[0:1], 0
	s_waitcnt vmcnt(0)
	v_cmp_lt_u32_e32 vcc, v1, v3
	s_and_saveexec_b64 s[16:17], vcc
	s_cbranch_execz .LBB0_98
	s_add_u32 s14, s86, 0x200
	s_addc_u32 s15, s87, 0
	s_mov_b32 s3, 1
	s_mov_b64 s[18:19], 0
	s_branch .LBB0_91

; __device__ __forceinline__ unsigned xb_ld(unsigned* p)              { return __hip_atomic_load(p, __ATOMIC_RELAXED, __HIP_MEMORY_SCOPE_AGENT); }
; #define XB_SPIN(cond, bar) do { unsigned _sp = 0; while (cond) { __builtin_amdgcn_s_sleep(1); \
;     if ((++_sp & 255u) == 0u) { if (xb_ld(&(bar)[XB_TMO])) break; if (_sp > XB_SPIN_CAP) { atomicAdd(&(bar)[XB_TMO], 1u); break; } } } } while (0)
; __device__ __forceinline__ void xcd_barrier(const XcdBarrier& b) {
;     ...
;             else XB_SPIN(xb_ld(&bar[XB_TOPGEN]) == tg, bar);
.LBB0_93:
	global_load_dword v1, v0, s[12:13] sc1
	s_add_i32 s3, s3, 1
	s_mov_b64 s[0:1], -1
	s_waitcnt vmcnt(0)
	v_cmp_ge_u32_e32 vcc, v1, v3
	s_orn2_b64 s[24:25], vcc, exec
	s_branch .LBB0_90

;     __device__ __forceinline__ bool run(const f32x4 (&v)[2][2][4][2], const Unit& u, int wr, int wc, int fr, int fq, PG8_LAS unsigned char* lds, int wid, int lane) const {
;     ...
;             __builtin_amdgcn_fence(__ATOMIC_ACQUIRE, "agent");
;             if (lane == 0) flag[0] = dead ? 1u : 0u;
.LBB0_314:
	s_waitcnt vmcnt(0)
	s_and_b64 exec, exec, s[8:9]
	v_cndmask_b32_e64 v128, 0, 1, s[10:11]
	v_mov_b32_e32 v129, 0
	ds_write_b32 v129, v128 offset:10240

; __device__ __forceinline__ unsigned xb_ld(unsigned* p)              { return __hip_atomic_load(p, __ATOMIC_RELAXED, __HIP_MEMORY_SCOPE_AGENT); }
; __device__ __forceinline__ unsigned xb_add(unsigned* p, unsigned v) { return __hip_atomic_fetch_add(p, v, __ATOMIC_RELAXED, __HIP_MEMORY_SCOPE_AGENT); }
; #define XB_SPIN(cond, bar) do { unsigned _sp = 0; while (cond) { __builtin_amdgcn_s_sleep(1); \
;     if ((++_sp & 255u) == 0u) { if (xb_ld(&(bar)[XB_TMO])) break; if (_sp > XB_SPIN_CAP) { atomicAdd(&(bar)[XB_TMO], 1u); break; } } } } while (0)
; __device__ __forceinline__ void xcd_barrier(const XcdBarrier& b) {
;     ...
;         const unsigned old = xb_add(&bar[XB_XSUB(b.x)], 1u);
;         const unsigned gen = old / nloc;
;         if (old + 1u == (gen + 1u) * nloc) {
;             __builtin_amdgcn_fence(__ATOMIC_RELEASE, "agent");
;             asm volatile("s_waitcnt vmcnt(0)" ::: "memory");
;             const unsigned og = xb_add(&bar[XB_TOP], 1u);
;             const unsigned tg = og / nx;
;             if (og + 1u == (tg + 1u) * nx) xb_add(&bar[XB_TOPGEN], 1u);
;             else XB_SPIN(xb_ld(&bar[XB_TOPGEN]) == tg, bar);
;             __builtin_amdgcn_fence(__ATOMIC_ACQUIRE, "agent");
;             xb_add(&bar[XB_XGEN(b.x)], 1u);
;             asm volatile("s_waitcnt vmcnt(0)" ::: "memory");
;         } else {
;             XB_SPIN(xb_ld(&bar[XB_XGEN(b.x)]) == gen, bar);
;             __builtin_amdgcn_fence(__ATOMIC_ACQUIRE, "agent");
;             asm volatile("s_waitcnt vmcnt(0)" ::: "memory");
;         }
.LBB0_1811:
	s_or_b64 exec, exec, s[8:9]
	s_waitcnt vmcnt(0)
	v_readfirstlane_b32 s0, v3
	v_add_u32_e32 v5, s0, v1
	v_readlane_b32 s0, v244, 63
	v_add_u32_e32 v3, 1, v5
	v_mov_b32_e32 v1, s0
	v_mad_u32_u24 v2, v1, v2, v2
	s_add_i32 s0, s0, 1
	v_writelane_b32 v244, s0, 63
	v_cmp_ne_u32_e32 vcc, v3, v2
	s_and_saveexec_b64 s[0:1], vcc
	s_xor_b64 s[8:9], exec, s[0:1]
	s_cbranch_execz .LBB0_1825
	s_waitcnt lgkmcnt(0)
	buffer_inv sc1
	v_mad_u32_u24 v3, v1, v0, v0
	v_mov_b32_e32 v0, 0x3400
	global_load_dword v0, v0, s[86:87] sc1
	s_add_u32 s12, s86, 0x3400
	s_addc_u32 s13, s87, 0
	s_waitcnt vmcnt(0)
	v_cmp_lt_u32_e32 vcc, v0, v3
	s_and_saveexec_b64 s[10:11], vcc
	s_cbranch_execz .LBB0_1824
	s_mov_b32 s3, 1
	s_mov_b64 s[14:15], 0
	v_mov_b32_e32 v0, 0
	s_branch .LBB0_1815

; __device__ __forceinline__ unsigned xb_ld(unsigned* p)              { return __hip_atomic_load(p, __ATOMIC_RELAXED, __HIP_MEMORY_SCOPE_AGENT); }
; #define XB_SPIN(cond, bar) do { unsigned _sp = 0; while (cond) { __builtin_amdgcn_s_sleep(1); \
;     if ((++_sp & 255u) == 0u) { if (xb_ld(&(bar)[XB_TMO])) break; if (_sp > XB_SPIN_CAP) { atomicAdd(&(bar)[XB_TMO], 1u); break; } } } } while (0)
; __device__ __forceinline__ void xcd_barrier(const XcdBarrier& b) {
;     ...
;             XB_SPIN(xb_ld(&bar[XB_XGEN(b.x)]) == gen, bar);
.LBB0_1817:
	global_load_dword v2, v0, s[12:13] sc1
	s_add_i32 s3, s3, 1
	s_mov_b64 s[18:19], -1
	s_waitcnt vmcnt(0)
	v_cmp_ge_u32_e32 vcc, v2, v3
	s_orn2_b64 s[0:1], vcc, exec
	s_branch .LBB0_1814

; __device__ __forceinline__ unsigned xb_ld(unsigned* p)              { return __hip_atomic_load(p, __ATOMIC_RELAXED, __HIP_MEMORY_SCOPE_AGENT); }
; __device__ __forceinline__ unsigned xb_add(unsigned* p, unsigned v) { return __hip_atomic_fetch_add(p, v, __ATOMIC_RELAXED, __HIP_MEMORY_SCOPE_AGENT); }
; #define XB_SPIN(cond, bar) do { unsigned _sp = 0; while (cond) { __builtin_amdgcn_s_sleep(1); \
;     if ((++_sp & 255u) == 0u) { if (xb_ld(&(bar)[XB_TMO])) break; if (_sp > XB_SPIN_CAP) { atomicAdd(&(bar)[XB_TMO], 1u); break; } } } } while (0)
; __device__ __forceinline__ void xcd_barrier(const XcdBarrier& b) {
;     ...
;             const unsigned og = xb_add(&bar[XB_TOP], 1u);
;             const unsigned tg = og / nx;
;             if (og + 1u == (tg + 1u) * nx) xb_add(&bar[XB_TOPGEN], 1u);
;             else XB_SPIN(xb_ld(&bar[XB_TOPGEN]) == tg, bar);
;             __builtin_amdgcn_fence(__ATOMIC_ACQUIRE, "agent");
.LBB0_1828:
	s_or_b64 exec, exec, s[8:9]
	s_waitcnt vmcnt(0)
	v_readfirstlane_b32 s0, v2
	s_add_u32 s10, s86, 0x3400
	s_addc_u32 s11, s87, 0
	v_add_u32_e32 v1, s0, v1
	v_add_u32_e32 v4, 1, v1
	s_mov_b64 s[0:1], 0
	v_readlane_b32 s8, v244, 63
	s_nop 0
	v_mul_u32_u24_e32 v0, s8, v0
	v_cmp_ne_u32_e32 vcc, v4, v0
	v_mov_b32_e32 v3, v0
	v_mov_b64_e32 v[0:1], s[10:11]
	s_and_saveexec_b64 s[8:9], vcc
	s_cbranch_execz .LBB0_1840
	v_mov_b32_e32 v0, 0
	global_load_dword v1, v0, s[10:11] sc1
	s_mov_b64 s[0:1], 0
	s_waitcnt vmcnt(0)
	v_cmp_lt_u32_e32 vcc, v1, v3
	s_and_saveexec_b64 s[14:15], vcc
	s_cbranch_execz .LBB0_1839
	s_add_u32 s12, s86, 0x200
	s_addc_u32 s13, s87, 0
	s_mov_b32 s3, 1
	s_mov_b64 s[16:17], 0
	s_branch .LBB0_1832

; __device__ __forceinline__ unsigned xb_ld(unsigned* p)              { return __hip_atomic_load(p, __ATOMIC_RELAXED, __HIP_MEMORY_SCOPE_AGENT); }
; #define XB_SPIN(cond, bar) do { unsigned _sp = 0; while (cond) { __builtin_amdgcn_s_sleep(1); \
;     if ((++_sp & 255u) == 0u) { if (xb_ld(&(bar)[XB_TMO])) break; if (_sp > XB_SPIN_CAP) { atomicAdd(&(bar)[XB_TMO], 1u); break; } } } } while (0)
; __device__ __forceinline__ void xcd_barrier(const XcdBarrier& b) {
;     ...
;             else XB_SPIN(xb_ld(&bar[XB_TOPGEN]) == tg, bar);
.LBB0_1834:
	global_load_dword v1, v0, s[10:11] sc1
	s_add_i32 s3, s3, 1
	s_mov_b64 s[0:1], -1
	s_waitcnt vmcnt(0)
	v_cmp_ge_u32_e32 vcc, v1, v3
	s_orn2_b64 s[22:23], vcc, exec
	s_branch .LBB0_1831

;     __device__ __forceinline__ bool run(const f32x4 (&v)[2][2][4][2], const Unit& u, int wr, int wc, int fr, int fq, PG8_LAS unsigned char* lds, int wid, int lane) const {
;     ...
;             __builtin_amdgcn_fence(__ATOMIC_ACQUIRE, "agent");
;             if (lane == 0) flag[0] = dead ? 1u : 0u;
.LBB0_1911:
	s_waitcnt vmcnt(0)
	s_and_b64 exec, exec, s[6:7]
	v_cndmask_b32_e64 v128, 0, 1, s[8:9]
	v_mov_b32_e32 v129, 0
	ds_write_b32 v129, v128 offset:10240

; __device__ __forceinline__ unsigned xb_ld(unsigned* p)              { return __hip_atomic_load(p, __ATOMIC_RELAXED, __HIP_MEMORY_SCOPE_AGENT); }
; __device__ __forceinline__ unsigned xb_add(unsigned* p, unsigned v) { return __hip_atomic_fetch_add(p, v, __ATOMIC_RELAXED, __HIP_MEMORY_SCOPE_AGENT); }
; #define XB_SPIN(cond, bar) do { unsigned _sp = 0; while (cond) { __builtin_amdgcn_s_sleep(1); \
;     if ((++_sp & 255u) == 0u) { if (xb_ld(&(bar)[XB_TMO])) break; if (_sp > XB_SPIN_CAP) { atomicAdd(&(bar)[XB_TMO], 1u); break; } } } } while (0)
; __device__ __forceinline__ void xcd_barrier(const XcdBarrier& b) {
;     ...
;         const unsigned old = xb_add(&bar[XB_XSUB(b.x)], 1u);
;         const unsigned gen = old / nloc;
;         if (old + 1u == (gen + 1u) * nloc) {
;             __builtin_amdgcn_fence(__ATOMIC_RELEASE, "agent");
;             asm volatile("s_waitcnt vmcnt(0)" ::: "memory");
;             const unsigned og = xb_add(&bar[XB_TOP], 1u);
;             const unsigned tg = og / nx;
;             if (og + 1u == (tg + 1u) * nx) xb_add(&bar[XB_TOPGEN], 1u);
;             else XB_SPIN(xb_ld(&bar[XB_TOPGEN]) == tg, bar);
;             __builtin_amdgcn_fence(__ATOMIC_ACQUIRE, "agent");
;             xb_add(&bar[XB_XGEN(b.x)], 1u);
;             asm volatile("s_waitcnt vmcnt(0)" ::: "memory");
;         } else {
;             XB_SPIN(xb_ld(&bar[XB_XGEN(b.x)]) == gen, bar);
;             __builtin_amdgcn_fence(__ATOMIC_ACQUIRE, "agent");
;             asm volatile("s_waitcnt vmcnt(0)" ::: "memory");
;         }
.LBB0_1936:
	s_or_b64 exec, exec, s[8:9]
	s_waitcnt vmcnt(0)
	v_readfirstlane_b32 s0, v3
	v_add_u32_e32 v5, s0, v1
	v_readlane_b32 s0, v244, 63
	v_add_u32_e32 v3, 1, v5
	v_mov_b32_e32 v1, s0
	v_mad_u32_u24 v2, v1, v2, v2
	s_add_i32 s0, s0, 1
	v_writelane_b32 v244, s0, 63
	v_cmp_ne_u32_e32 vcc, v3, v2
	s_and_saveexec_b64 s[0:1], vcc
	s_xor_b64 s[8:9], exec, s[0:1]
	s_cbranch_execz .LBB0_1950
	s_waitcnt lgkmcnt(0)
	buffer_inv sc1
	v_mad_u32_u24 v3, v1, v0, v0
	v_mov_b32_e32 v0, 0x3400
	global_load_dword v0, v0, s[86:87] sc1
	s_add_u32 s12, s86, 0x3400
	s_addc_u32 s13, s87, 0
	s_waitcnt vmcnt(0)
	v_cmp_lt_u32_e32 vcc, v0, v3
	s_and_saveexec_b64 s[10:11], vcc
	s_cbranch_execz .LBB0_1949
	s_mov_b32 s22, 1
	s_mov_b64 s[14:15], 0
	v_mov_b32_e32 v0, 0
	s_branch .LBB0_1940

; __device__ __forceinline__ unsigned xb_ld(unsigned* p)              { return __hip_atomic_load(p, __ATOMIC_RELAXED, __HIP_MEMORY_SCOPE_AGENT); }
; #define XB_SPIN(cond, bar) do { unsigned _sp = 0; while (cond) { __builtin_amdgcn_s_sleep(1); \
;     if ((++_sp & 255u) == 0u) { if (xb_ld(&(bar)[XB_TMO])) break; if (_sp > XB_SPIN_CAP) { atomicAdd(&(bar)[XB_TMO], 1u); break; } } } } while (0)
; __device__ __forceinline__ void xcd_barrier(const XcdBarrier& b) {
;     ...
;             XB_SPIN(xb_ld(&bar[XB_XGEN(b.x)]) == gen, bar);
.LBB0_1942:
	global_load_dword v2, v0, s[12:13] sc1
	s_add_i32 s22, s22, 1
	s_mov_b64 s[18:19], -1
	s_waitcnt vmcnt(0)
	v_cmp_ge_u32_e32 vcc, v2, v3
	s_orn2_b64 s[0:1], vcc, exec
	s_branch .LBB0_1939

; __device__ __forceinline__ unsigned xb_ld(unsigned* p)              { return __hip_atomic_load(p, __ATOMIC_RELAXED, __HIP_MEMORY_SCOPE_AGENT); }
; __device__ __forceinline__ unsigned xb_add(unsigned* p, unsigned v) { return __hip_atomic_fetch_add(p, v, __ATOMIC_RELAXED, __HIP_MEMORY_SCOPE_AGENT); }
; #define XB_SPIN(cond, bar) do { unsigned _sp = 0; while (cond) { __builtin_amdgcn_s_sleep(1); \
;     if ((++_sp & 255u) == 0u) { if (xb_ld(&(bar)[XB_TMO])) break; if (_sp > XB_SPIN_CAP) { atomicAdd(&(bar)[XB_TMO], 1u); break; } } } } while (0)
; __device__ __forceinline__ void xcd_barrier(const XcdBarrier& b) {
;     ...
;             const unsigned og = xb_add(&bar[XB_TOP], 1u);
;             const unsigned tg = og / nx;
;             if (og + 1u == (tg + 1u) * nx) xb_add(&bar[XB_TOPGEN], 1u);
;             else XB_SPIN(xb_ld(&bar[XB_TOPGEN]) == tg, bar);
;             __builtin_amdgcn_fence(__ATOMIC_ACQUIRE, "agent");
.LBB0_1953:
	s_or_b64 exec, exec, s[8:9]
	s_waitcnt vmcnt(0)
	v_readfirstlane_b32 s0, v2
	s_add_u32 s10, s86, 0x3400
	s_addc_u32 s11, s87, 0
	v_add_u32_e32 v1, s0, v1
	v_add_u32_e32 v4, 1, v1
	s_mov_b64 s[0:1], 0
	v_readlane_b32 s8, v244, 63
	s_nop 0
	v_mul_u32_u24_e32 v0, s8, v0
	v_cmp_ne_u32_e32 vcc, v4, v0
	v_mov_b32_e32 v3, v0
	v_mov_b64_e32 v[0:1], s[10:11]
	s_and_saveexec_b64 s[8:9], vcc
	s_cbranch_execz .LBB0_1965
	v_mov_b32_e32 v0, 0
	global_load_dword v1, v0, s[10:11] sc1
	s_mov_b64 s[0:1], 0
	s_waitcnt vmcnt(0)
	v_cmp_lt_u32_e32 vcc, v1, v3
	s_and_saveexec_b64 s[14:15], vcc
	s_cbranch_execz .LBB0_1964
	s_add_u32 s12, s86, 0x200
	s_addc_u32 s13, s87, 0
	s_mov_b32 s24, 1
	s_mov_b64 s[16:17], 0
	s_branch .LBB0_1957

; __device__ __forceinline__ unsigned xb_ld(unsigned* p)              { return __hip_atomic_load(p, __ATOMIC_RELAXED, __HIP_MEMORY_SCOPE_AGENT); }
; #define XB_SPIN(cond, bar) do { unsigned _sp = 0; while (cond) { __builtin_amdgcn_s_sleep(1); \
;     if ((++_sp & 255u) == 0u) { if (xb_ld(&(bar)[XB_TMO])) break; if (_sp > XB_SPIN_CAP) { atomicAdd(&(bar)[XB_TMO], 1u); break; } } } } while (0)
; __device__ __forceinline__ void xcd_barrier(const XcdBarrier& b) {
;     ...
;             else XB_SPIN(xb_ld(&bar[XB_TOPGEN]) == tg, bar);
.LBB0_1959:
	global_load_dword v1, v0, s[10:11] sc1
	s_add_i32 s24, s24, 1
	s_mov_b64 s[0:1], -1
	s_waitcnt vmcnt(0)
	v_cmp_ge_u32_e32 vcc, v1, v3
	s_orn2_b64 s[22:23], vcc, exec
	s_branch .LBB0_1956
